# FFN-up GEMM epilogue: conv-tap weights requested one tile ahead into registers unused by the K-loop and epilogue, copied at the epilogue head; the two vmcnt(0) waits behind the old in-epilogue loads r
# baseline (speedup 1.0000x reference)
; #define PG8_STAGE(bufoff, gbase, voff) do { _Pragma("unroll") for (int _i = 0; _i < 2; ++_i) \
;         __builtin_amdgcn_global_load_lds((const unsigned*)((const char*)(gbase) + (voff)[_i]), (PG8_LAS unsigned*)(lds + (bufoff) + ldsw + _i * 8192), 16, 0, 0); } while (0)
; #define PG8_WAIT_V(n) asm volatile("s_waitcnt vmcnt(" #n ")" ::: "memory")
; #define PG8_BAR __builtin_amdgcn_s_barrier()
; template <class Epi, class Sched, bool ALIGN_EPI = false, bool SP2 = false>
; __device__ __forceinline__ void gemm_phase(PG8_LAS unsigned char* lds, const Gemm g, const Sched& S, const Epi& E, int wave_idx  ) {
;     ...
;         PG8_STAGE(PG8_SB(0, 0), cB, voffB); PG8_STAGE(PG8_SB(0, 1), cB + hstep, voffB); PG8_STAGE(PG8_SA(0, 0), cA, voffA); PG8_STAGE(PG8_SA(0, 1), cA + hstep, voffA);
;         if (wr == 1) PG8_BAR;
;         PG8_WAIT_V(2); PG8_BAR;
;         PG8_STAGE(PG8_SB(1, 0), cB + kstep, voffB); PG8_STAGE(PG8_SA(1, 0), cA + kstep, voffA); PG8_STAGE(PG8_SB(1, 1), cB + hstep + kstep, voffB);
;         PG8_WAIT_V(6); PG8_BAR;
;     } else {
;         PG8_STAGE(PG8_SB(0, 0), cB, voffB); PG8_STAGE(PG8_SA(0, 0), cA, voffA); PG8_STAGE(PG8_SB(0, 1), cB + hstep, voffB); PG8_STAGE(PG8_SA(0, 1), cA + hstep, voffA);
;         if (wr == 1) PG8_BAR;
;         PG8_WAIT_V(4); PG8_BAR;
;         PG8_STAGE(PG8_SB(1, 0), cB + kstep, voffB); PG8_STAGE(PG8_SA(1, 0), cA + kstep, voffA); PG8_STAGE(PG8_SB(1, 1), cB + hstep + kstep, voffB);
;         PG8_WAIT_V(6); PG8_BAR;
;     __device__ __forceinline__ void operator()(const f32x4 (&acc)[2][2][4][2], const Unit& u, int wr, int wc, int fr, int fq) const {
;     ...
;         for (int h = 0; h < 2; ++h) { const f32x4 a = *(const f32x4*)(fw + c0 + 4 * h), b = *(const f32x4*)(fw + dff + c0 + 4 * h), d = *(const f32x4*)(fw + 2 * dff + c0 + 4 * h);
; #pragma unroll
;             for (int q = 0; q < 4; ++q) { w0[4 * h + q] = a[q]; w1[4 * h + q] = b[q]; w2[4 * h + q] = d[q]; } }
.LBB0_1841:
	v_and_b32_e32 v18, 15, v8
	v_lshrrev_b32_e32 v9, 1, v8
	v_or_b32_e32 v188, s23, v18
	v_and_b32_e32 v19, 24, v9
	v_lshlrev_b32_e32 v9, 6, v188
	v_lshlrev_b32_e32 v20, 1, v19
	s_movk_i32 s8, 0x3c0
	v_lshlrev_b32_e32 v21, 2, v188
	v_and_or_b32 v9, v9, s8, v20
	v_and_b32_e32 v21, 32, v21
	v_lshlrev_b32_e32 v8, 2, v8
	v_lshl_add_u64 v[10:11], s[60:61], 0, v[0:1]
	v_mov_b32_e32 v159, v1
	v_bitop3_b32 v21, v9, s26, v21 bitop3:0xde
	v_lshl_or_b32 v9, v18, 6, v20
	v_and_b32_e32 v8, 32, v8
	v_lshl_add_u64 v[12:13], s[60:61], 0, v[158:159]
	v_mov_b32_e32 v163, v1
	v_bitop3_b32 v189, v9, s30, v8 bitop3:0xde
	v_lshl_add_u64 v[8:9], v[10:11], 0, s[34:35]
	s_add_i32 m0, s59, 0x18400
	v_lshl_add_u64 v[14:15], s[64:65], 0, v[162:163]
	v_mov_b32_e32 v161, v1
	s_waitcnt vmcnt(2)
	s_barrier
	global_load_lds_dwordx4 v[8:9], off
	v_lshl_add_u64 v[8:9], v[12:13], 0, s[34:35]
	s_add_i32 m0, s59, 0x1a400
	s_add_i32 s85, s59, 0x8400
	v_lshl_add_u64 v[16:17], s[64:65], 0, v[160:161]
	global_load_lds_dwordx4 v[8:9], off
	v_lshl_add_u64 v[8:9], v[14:15], 0, s[34:35]
	s_mov_b32 m0, s85
	s_add_i32 s86, s59, 0xa400
	global_load_lds_dwordx4 v[8:9], off
	v_lshl_add_u64 v[8:9], v[16:17], 0, s[34:35]
	s_mov_b32 m0, s86
	s_mov_b32 s87, 0
	global_load_lds_dwordx4 v[8:9], off
	v_lshl_add_u64 v[8:9], s[68:69], 0, v[0:1]
	s_add_i32 m0, s59, 0x1c400
	v_cmp_eq_u32_e64 s[40:41], 0, v18
	global_load_lds_dwordx4 v[8:9], off
	v_lshl_add_u64 v[8:9], s[68:69], 0, v[158:159]
	s_add_i32 m0, s59, 0x1e400
	v_cmp_lt_u32_e64 s[42:43], 1, v18
	global_load_lds_dwordx4 v[8:9], off
	v_lshlrev_b32_e32 v8, 14, v5
	v_and_b32_e32 v8, 0xffff8000, v8
	v_lshl_add_u32 v6, v6, 11, v8
	v_and_b32_e32 v5, 1, v5
	v_lshl_or_b32 v5, v5, 6, v6
	v_lshl_add_u32 v164, v7, 1, v5
	v_lshlrev_b32_e32 v5, 14, v2
	v_and_b32_e32 v5, 0xffff8000, v5
	s_waitcnt vmcnt(6)
	v_lshl_add_u32 v3, v3, 11, v5
	v_and_b32_e32 v2, 1, v2
	v_lshl_or_b32 v2, v2, 6, v3
	v_cmp_gt_u32_e64 s[44:45], 2, v18
	v_cmp_lt_u32_e64 s[46:47], 13, v18
	v_or_b32_e32 v190, s27, v19
	v_mov_b32_e32 v165, v1
	v_lshl_add_u32 v166, v4, 1, v2
	v_mov_b32_e32 v167, v1
	v_add_u32_e32 v191, 0, v21
	s_mov_b32 s28, s84
	s_mov_b32 s20, s58
	s_mov_b64 s[8:9], s[60:61]
	s_mov_b64 s[16:17], s[64:65]
	v_lshl_or_b32 v225, s28, 7, v190
	v_lshlrev_b32_e32 v225, 2, v225
	global_load_dwordx2 v[218:219], v225, s[10:11]
	global_load_dwordx2 v[230:231], v225, s[10:11] offset:8
	global_load_dwordx2 v[232:233], v225, s[10:11] offset:16
	global_load_dwordx2 v[234:235], v225, s[10:11] offset:24
	global_load_dwordx2 v[236:237], v225, s[54:55]
	global_load_dwordx2 v[238:239], v225, s[54:55] offset:8
	global_load_dwordx2 v[240:241], v225, s[54:55] offset:16
	global_load_dwordx2 v[242:243], v225, s[54:55] offset:24
	global_load_dwordx2 v[244:245], v225, s[56:57]
	global_load_dwordx2 v[246:247], v225, s[56:57] offset:8
	global_load_dwordx2 v[250:251], v225, s[56:57] offset:16
	global_load_dword v249, v225, s[56:57] offset:24
	global_load_dword v252, v225, s[56:57] offset:28
	s_barrier
	s_branch .LBB0_1844

;     __device__ __forceinline__ void operator()(const f32x4 (&acc)[2][2][4][2], const Unit& u, int wr, int wc, int fr, int fq) const {
;         const int row0 = u.pm * BM + wr * 64 + fr, c0 = u.pn * HALF + wc * 32 + 8 * fq;
;         float w0[8], w1[8], w2[8];
; #pragma unroll
;         for (int h = 0; h < 2; ++h) { const f32x4 a = *(const f32x4*)(fw + c0 + 4 * h), b = *(const f32x4*)(fw + dff + c0 + 4 * h), d = *(const f32x4*)(fw + 2 * dff + c0 + 4 * h);
; #pragma unroll
;             for (int q = 0; q < 4; ++q) { w0[4 * h + q] = a[q]; w1[4 * h + q] = b[q]; w2[4 * h + q] = d[q]; } }
; #pragma unroll
;         for (int ai = 0; ai < 2; ++ai) {
;             float p1[8], p2[8];
; #pragma unroll
;             for (int q = 0; q < 8; ++q) { p1[q] = 0.f; p2[q] = 0.f; }
; #pragma unroll
;             for (int m = 0; m < 4; ++m) { const size_t row = (size_t)(row0 + ai * HALF + m * 16);
;                 float x[8], mu[8], y[8];
; #pragma unroll
;                 for (int q = 0; q < 8; ++q) { x[q] = acc[ai][0][m][q >> 2][q & 3]; mu[q] = acc[ai][1][m][q >> 2][q & 3]; }
; #pragma unroll
;                 for (int q = 0; q < 8; ++q) {
;                     const float r1 = __int_as_float(__builtin_amdgcn_mov_dpp(__float_as_int(x[q]), 0x121, 0xF, 0xF, true));
;                     const float r2 = __int_as_float(__builtin_amdgcn_mov_dpp(__float_as_int(x[q]), 0x122, 0xF, 0xF, true));
;                     const float x1 = (fr == 0) ? p1[q] : r1, x2 = (fr < 2) ? p2[q] : r2;
.LBB0_1850:
	v_lshl_or_b32 v168, s28, 7, v190
	v_ashrrev_i32_e32 v169, 31, v168
	v_mov_b64_e32 v[78:79], v[218:219]
	v_mov_b64_e32 v[80:81], v[230:231]
	v_mov_b64_e32 v[66:67], v[232:233]
	v_mov_b64_e32 v[68:69], v[234:235]
	v_mov_b64_e32 v[82:83], v[236:237]
	v_mov_b64_e32 v[84:85], v[238:239]
	v_mov_b64_e32 v[70:71], v[240:241]
	v_mov_b64_e32 v[72:73], v[242:243]
	v_mov_b64_e32 v[90:91], v[244:245]
	v_mov_b64_e32 v[92:93], v[246:247]
	v_mov_b64_e32 v[74:75], v[250:251]
	v_mov_b32_e32 v76, v249
	v_mov_b32_e32 v77, v252
	s_cmp_lg_u64 s[48:49], 0
	s_cselect_b32 s32, s70, s28
	v_lshl_or_b32 v225, s32, 7, v190
	v_lshlrev_b32_e32 v225, 2, v225
	global_load_dwordx2 v[218:219], v225, s[10:11]
	global_load_dwordx2 v[230:231], v225, s[10:11] offset:8
	global_load_dwordx2 v[232:233], v225, s[10:11] offset:16
	global_load_dwordx2 v[234:235], v225, s[10:11] offset:24
	global_load_dwordx2 v[236:237], v225, s[54:55]
	global_load_dwordx2 v[238:239], v225, s[54:55] offset:8
	global_load_dwordx2 v[240:241], v225, s[54:55] offset:16
	global_load_dwordx2 v[242:243], v225, s[54:55] offset:24
	global_load_dwordx2 v[244:245], v225, s[56:57]
	global_load_dwordx2 v[246:247], v225, s[56:57] offset:8
	global_load_dwordx2 v[250:251], v225, s[56:57] offset:16
	global_load_dword v249, v225, s[56:57] offset:24
	global_load_dword v252, v225, s[56:57] offset:28
	v_lshl_add_u32 v192, s20, 8, v188
	v_mov_b32_dpp v184, v150 row_ror:1 row_mask:0xf bank_mask:0xf bound_ctrl:1
	v_mov_b32_dpp v182, v150 row_ror:2 row_mask:0xf bank_mask:0xf bound_ctrl:1
	v_mov_b32_dpp v185, v151 row_ror:1 row_mask:0xf bank_mask:0xf bound_ctrl:1
	v_mov_b32_dpp v183, v151 row_ror:2 row_mask:0xf bank_mask:0xf bound_ctrl:1
	v_mov_b32_dpp v180, v152 row_ror:1 row_mask:0xf bank_mask:0xf bound_ctrl:1
	v_mov_b32_dpp v178, v152 row_ror:2 row_mask:0xf bank_mask:0xf bound_ctrl:1
	v_mov_b32_dpp v181, v153 row_ror:1 row_mask:0xf bank_mask:0xf bound_ctrl:1
	v_mov_b32_dpp v179, v153 row_ror:2 row_mask:0xf bank_mask:0xf bound_ctrl:1
	v_mov_b32_dpp v176, v146 row_ror:1 row_mask:0xf bank_mask:0xf bound_ctrl:1
	v_mov_b32_dpp v174, v146 row_ror:2 row_mask:0xf bank_mask:0xf bound_ctrl:1
	v_mov_b32_dpp v177, v147 row_ror:1 row_mask:0xf bank_mask:0xf bound_ctrl:1
	v_mov_b32_dpp v175, v147 row_ror:2 row_mask:0xf bank_mask:0xf bound_ctrl:1
	v_mov_b32_dpp v172, v148 row_ror:1 row_mask:0xf bank_mask:0xf bound_ctrl:1
	v_mov_b32_dpp v170, v148 row_ror:2 row_mask:0xf bank_mask:0xf bound_ctrl:1
	v_mov_b32_dpp v173, v149 row_ror:1 row_mask:0xf bank_mask:0xf bound_ctrl:1
	v_mov_b32_dpp v171, v149 row_ror:2 row_mask:0xf bank_mask:0xf bound_ctrl:1
	s_and_saveexec_b64 s[8:9], s[42:43]
	s_xor_b64 s[16:17], exec, s[8:9]
	s_cbranch_execz .LBB0_1852
; __device__ __forceinline__ unsigned cvt_pk_bf16(float lo, float hi) { unsigned r; asm volatile("v_cvt_pk_bf16_f32 %0, %1, %2" : "=v"(r) : "v"(lo), "v"(hi)); return r; }
; __device__ __forceinline__ f32x2 gelu_pk(f32x2 v) {
;     const f32x2 av = __builtin_elementwise_abs(v), d = av * 0.2316418882f + 1.0f;
;     f32x2 t; t.x = __builtin_amdgcn_rcpf(d.x); t.y = __builtin_amdgcn_rcpf(d.y);
;     f32x2 q = t * 0.5307027145f + (-0.7265760135f); q = q * t + 0.7107068705f; q = q * t + (-0.142248368f); q = q * t + 0.127414796f; q = q * t;
;     const f32x2 s = (v * v) * (-0.72134752044f);
;     f32x2 e; e.x = __builtin_amdgcn_exp2f(s.x); e.y = __builtin_amdgcn_exp2f(s.y);
;     const f32x2 m = v * (q * e), r = v - m;
;     f32x2 o; o.x = v.x < 0.f ? m.x : r.x; o.y = v.y < 0.f ? m.y : r.y; return o;
; }
;     __device__ __forceinline__ void operator()(const f32x4 (&acc)[2][2][4][2], const Unit& u, int wr, int wc, int fr, int fq) const {
;     ...
;                 for (int q = 0; q < 8; ++q) {
;                     const float r1 = __int_as_float(__builtin_amdgcn_mov_dpp(__float_as_int(x[q]), 0x121, 0xF, 0xF, true));
;                     const float r2 = __int_as_float(__builtin_amdgcn_mov_dpp(__float_as_int(x[q]), 0x122, 0xF, 0xF, true));
;                     const float x1 = (fr == 0) ? p1[q] : r1, x2 = (fr < 2) ? p2[q] : r2;
;                     y[q] = w0[q] * x2 + w1[q] * x1 + w2[q] * x[q]; p1[q] = r1; p2[q] = r2; }
; #pragma unroll
;                 for (int q = 0; q < 8; q += 2) { const f32x2 gq = gelu_pk((f32x2){y[q], y[q + 1]}); y[q] = gq.x * mu[q]; y[q + 1] = gq.y * mu[q + 1]; }
;                 const bool lo = (m == 0) && (fr < 2);
;                 if (!lo) { u32x4 w; w.x = cvt_pk_bf16(y[0], y[1]); w.y = cvt_pk_bf16(y[2], y[3]); w.z = cvt_pk_bf16(y[4], y[5]); w.w = cvt_pk_bf16(y[6], y[7]); *(u32x4*)(ACT + row * dff + c0) = w; }
	v_pk_mul_f32 v[194:195], v[68:69], v[170:171]
	s_mov_b32 s20, 0x3e6d3388
	v_pk_fma_f32 v[194:195], v[72:73], v[172:173], v[194:195]
	s_mov_b32 s28, 0xbf3a00e3
	v_pk_fma_f32 v[194:195], v[148:149], v[76:77], v[194:195]
	s_mov_b32 s8, 0xbf38aa3b
	v_and_b32_e32 v199, 0x7fffffff, v195
	v_and_b32_e32 v198, 0x7fffffff, v194
	v_pk_fma_f32 v[198:199], v[198:199], s[20:21], 1.0 op_sel_hi:[1,0,0]
	v_pk_mul_f32 v[196:197], v[194:195], v[194:195]
	v_rcp_f32_e32 v198, v198
	v_rcp_f32_e32 v199, v199
	v_mov_b64_e32 v[200:201], s[28:29]
	s_mov_b32 s28, 0x3f07dc22
	v_pk_mul_f32 v[196:197], v[196:197], s[8:9] op_sel_hi:[1,0]
	v_pk_fma_f32 v[202:203], v[198:199], s[28:29], v[200:201] op_sel_hi:[1,0,0]
	s_mov_b32 s78, 0x3f35f0e3
	v_exp_f32_e32 v196, v196
	v_exp_f32_e32 v197, v197
	v_pk_fma_f32 v[202:203], v[198:199], v[202:203], s[78:79] op_sel_hi:[1,1,0]
	s_mov_b32 s88, 0xbe11a98e
	v_pk_fma_f32 v[202:203], v[198:199], v[202:203], s[88:89] op_sel_hi:[1,1,0]
	s_mov_b32 s90, 0x3e027906
	v_pk_fma_f32 v[202:203], v[198:199], v[202:203], s[90:91] op_sel_hi:[1,1,0]
	v_pk_mul_f32 v[154:155], v[66:67], v[174:175]
	v_pk_mul_f32 v[198:199], v[198:199], v[202:203]
	v_pk_fma_f32 v[154:155], v[70:71], v[176:177], v[154:155]
	v_pk_mul_f32 v[196:197], v[196:197], v[198:199]
	v_cmp_gt_f32_e32 vcc, 0, v195
	v_pk_mul_f32 v[198:199], v[194:195], v[196:197]
	v_pk_fma_f32 v[196:197], v[194:195], v[196:197], v[194:195] neg_lo:[1,0,0] neg_hi:[1,0,0]
	v_pk_fma_f32 v[154:155], v[146:147], v[74:75], v[154:155]
	v_cndmask_b32_e32 v193, v197, v199, vcc
	v_cmp_gt_f32_e32 vcc, 0, v194
	v_and_b32_e32 v197, 0x7fffffff, v155
	v_pk_mul_f32 v[156:157], v[80:81], v[178:179]
	v_cndmask_b32_e32 v194, v196, v198, vcc
	v_and_b32_e32 v196, 0x7fffffff, v154
	v_pk_fma_f32 v[196:197], v[196:197], s[20:21], 1.0 op_sel_hi:[1,0,0]
	v_mul_f32_e32 v202, v140, v194
	v_rcp_f32_e32 v196, v196
	v_rcp_f32_e32 v197, v197
	v_pk_mul_f32 v[194:195], v[154:155], v[154:155]
	v_pk_fma_f32 v[156:157], v[84:85], v[180:181], v[156:157]
	v_pk_mul_f32 v[194:195], v[194:195], s[8:9] op_sel_hi:[1,0]
	v_pk_fma_f32 v[198:199], v[196:197], s[28:29], v[200:201] op_sel_hi:[1,0,0]
	v_exp_f32_e32 v194, v194
	v_exp_f32_e32 v195, v195
	v_pk_fma_f32 v[198:199], v[196:197], v[198:199], s[78:79] op_sel_hi:[1,1,0]
	v_cmp_gt_f32_e32 vcc, 0, v155
	v_pk_fma_f32 v[198:199], v[196:197], v[198:199], s[88:89] op_sel_hi:[1,1,0]
	v_pk_fma_f32 v[156:157], v[152:153], v[92:93], v[156:157]
	v_pk_fma_f32 v[198:199], v[196:197], v[198:199], s[90:91] op_sel_hi:[1,1,0]
	v_pk_mul_f32 v[186:187], v[78:79], v[182:183]
	v_pk_mul_f32 v[196:197], v[196:197], v[198:199]
	v_pk_fma_f32 v[186:187], v[82:83], v[184:185], v[186:187]
	v_pk_mul_f32 v[194:195], v[194:195], v[196:197]
	v_pk_fma_f32 v[186:187], v[150:151], v[90:91], v[186:187]
	v_pk_mul_f32 v[196:197], v[154:155], v[194:195]
	v_pk_fma_f32 v[194:195], v[154:155], v[194:195], v[154:155] neg_lo:[1,0,0] neg_hi:[1,0,0]
	v_mul_f32_e32 v193, v141, v193
	v_cndmask_b32_e32 v155, v195, v197, vcc
	v_cmp_gt_f32_e32 vcc, 0, v154
	v_and_b32_e32 v195, 0x7fffffff, v157
	v_mul_f32_e32 v198, v139, v155
	v_cndmask_b32_e32 v154, v194, v196, vcc
	v_and_b32_e32 v194, 0x7fffffff, v156
	v_pk_fma_f32 v[194:195], v[194:195], s[20:21], 1.0 op_sel_hi:[1,0,0]
	v_mul_f32_e32 v199, v138, v154
	v_rcp_f32_e32 v194, v194
	v_rcp_f32_e32 v195, v195
	v_pk_mul_f32 v[154:155], v[156:157], v[156:157]
	v_cmp_gt_f32_e32 vcc, 0, v157
	v_pk_mul_f32 v[154:155], v[154:155], s[8:9] op_sel_hi:[1,0]
	v_pk_fma_f32 v[196:197], v[194:195], s[28:29], v[200:201] op_sel_hi:[1,0,0]
	v_exp_f32_e32 v154, v154
	v_exp_f32_e32 v155, v155
	v_pk_fma_f32 v[196:197], v[194:195], v[196:197], s[78:79] op_sel_hi:[1,1,0]
	s_nop 0
	v_pk_fma_f32 v[196:197], v[194:195], v[196:197], s[88:89] op_sel_hi:[1,1,0]
	s_nop 0
	v_pk_fma_f32 v[196:197], v[194:195], v[196:197], s[90:91] op_sel_hi:[1,1,0]
	s_nop 0
	v_pk_mul_f32 v[194:195], v[194:195], v[196:197]
	s_nop 0
	v_pk_mul_f32 v[154:155], v[154:155], v[194:195]
	s_nop 0
	v_pk_mul_f32 v[194:195], v[156:157], v[154:155]
	v_pk_fma_f32 v[154:155], v[156:157], v[154:155], v[156:157] neg_lo:[1,0,0] neg_hi:[1,0,0]
	v_and_b32_e32 v157, 0x7fffffff, v187
	v_cndmask_b32_e32 v155, v155, v195, vcc
	v_cmp_gt_f32_e32 vcc, 0, v156
	v_and_b32_e32 v156, 0x7fffffff, v186
	v_pk_fma_f32 v[156:157], v[156:157], s[20:21], 1.0 op_sel_hi:[1,0,0]
	v_cndmask_b32_e32 v154, v154, v194, vcc
	v_rcp_f32_e32 v156, v156
	v_rcp_f32_e32 v157, v157
	v_mul_f32_e32 v196, v145, v155
	v_mul_f32_e32 v197, v144, v154
	v_pk_mul_f32 v[154:155], v[186:187], v[186:187]
	v_pk_fma_f32 v[194:195], v[156:157], s[28:29], v[200:201] op_sel_hi:[1,0,0]
	v_pk_mul_f32 v[154:155], v[154:155], s[8:9] op_sel_hi:[1,0]
	v_pk_fma_f32 v[194:195], v[156:157], v[194:195], s[78:79] op_sel_hi:[1,1,0]
	v_exp_f32_e32 v154, v154
	v_exp_f32_e32 v155, v155
	v_pk_fma_f32 v[194:195], v[156:157], v[194:195], s[88:89] op_sel_hi:[1,1,0]
	v_cmp_gt_f32_e32 vcc, 0, v187
	v_pk_fma_f32 v[194:195], v[156:157], v[194:195], s[90:91] op_sel_hi:[1,1,0]
	s_movk_i32 s8, 0x1600
	v_pk_mul_f32 v[156:157], v[156:157], v[194:195]
	s_nop 0
	v_pk_mul_f32 v[154:155], v[154:155], v[156:157]
	s_nop 0
	v_pk_mul_f32 v[156:157], v[186:187], v[154:155]
	v_pk_fma_f32 v[154:155], v[186:187], v[154:155], v[186:187] neg_lo:[1,0,0] neg_hi:[1,0,0]
	s_nop 0
	v_cndmask_b32_e32 v155, v155, v157, vcc
	v_cmp_gt_f32_e32 vcc, 0, v186
	v_mov_b64_e32 v[186:187], s[4:5]
	v_mul_f32_e32 v155, v143, v155
	v_cndmask_b32_e32 v154, v154, v156, vcc
	v_mul_f32_e32 v154, v142, v154
	v_mad_i64_i32 v[186:187], s[8:9], v192, s8, v[186:187]
	v_cvt_pk_bf16_f32 v154, v154, v155
	v_cvt_pk_bf16_f32 v155, v197, v196
	v_cvt_pk_bf16_f32 v156, v199, v198
	v_cvt_pk_bf16_f32 v157, v202, v193

; __device__ __forceinline__ unsigned cvt_pk_bf16(float lo, float hi) { unsigned r; asm volatile("v_cvt_pk_bf16_f32 %0, %1, %2" : "=v"(r) : "v"(lo), "v"(hi)); return r; }
;     __device__ __forceinline__ void operator()(const f32x4 (&acc)[2][2][4][2], const Unit& u, int wr, int wc, int fr, int fq) const {
;     ...
;             for (int m = 0; m < 4; ++m) { const size_t row = (size_t)(row0 + ai * HALF + m * 16);
;                 float x[8], mu[8], y[8];
; #pragma unroll
;                 for (int q = 0; q < 8; ++q) { x[q] = acc[ai][0][m][q >> 2][q & 3]; mu[q] = acc[ai][1][m][q >> 2][q & 3]; }
; #pragma unroll
;                 for (int q = 0; q < 8; ++q) {
;                     const float r1 = __int_as_float(__builtin_amdgcn_mov_dpp(__float_as_int(x[q]), 0x121, 0xF, 0xF, true));
;                     const float r2 = __int_as_float(__builtin_amdgcn_mov_dpp(__float_as_int(x[q]), 0x122, 0xF, 0xF, true));
;                     const float x1 = (fr == 0) ? p1[q] : r1, x2 = (fr < 2) ? p2[q] : r2;
;                     y[q] = w0[q] * x2 + w1[q] * x1 + w2[q] * x[q]; p1[q] = r1; p2[q] = r2; }
; #pragma unroll
;                 for (int q = 0; q < 8; q += 2) { const f32x2 gq = gelu_pk((f32x2){y[q], y[q + 1]}); y[q] = gq.x * mu[q]; y[q + 1] = gq.y * mu[q + 1]; }
;                 const bool lo = (m == 0) && (fr < 2);
;                 if (!lo) { u32x4 w; w.x = cvt_pk_bf16(y[0], y[1]); w.y = cvt_pk_bf16(y[2], y[3]); w.z = cvt_pk_bf16(y[4], y[5]); w.w = cvt_pk_bf16(y[6], y[7]); *(u32x4*)(ACT + row * dff + c0) = w; }
.LBB0_1854:
	s_or_b64 exec, exec, s[8:9]
	v_lshlrev_b64 v[138:139], 1, v[168:169]
	v_mov_b32_dpp v150, v134 row_ror:2 row_mask:0xf bank_mask:0xf bound_ctrl:1
	v_mov_b32_dpp v152, v135 row_ror:2 row_mask:0xf bank_mask:0xf bound_ctrl:1
	v_lshl_add_u64 v[140:141], v[186:187], 0, v[138:139]
	v_mov_b32_dpp v149, v134 row_ror:1 row_mask:0xf bank_mask:0xf bound_ctrl:1
	v_mov_b32_dpp v151, v135 row_ror:1 row_mask:0xf bank_mask:0xf bound_ctrl:1
	v_cndmask_b32_e64 v143, v152, v183, s[44:45]
	v_cndmask_b32_e64 v142, v150, v182, s[44:45]
	global_store_dwordx4 v[140:141], v[154:157], off
	v_cndmask_b32_e64 v141, v151, v185, s[40:41]
	v_cndmask_b32_e64 v140, v149, v184, s[40:41]
	v_pk_mul_f32 v[142:143], v[78:79], v[142:143]
	v_mov_b32_dpp v154, v136 row_ror:2 row_mask:0xf bank_mask:0xf bound_ctrl:1
	v_mov_b32_dpp v156, v137 row_ror:2 row_mask:0xf bank_mask:0xf bound_ctrl:1
	v_pk_fma_f32 v[140:141], v[82:83], v[140:141], v[142:143]
	v_mov_b32_dpp v153, v136 row_ror:1 row_mask:0xf bank_mask:0xf bound_ctrl:1
	v_mov_b32_dpp v155, v137 row_ror:1 row_mask:0xf bank_mask:0xf bound_ctrl:1
	v_cndmask_b32_e64 v143, v156, v179, s[44:45]
	v_cndmask_b32_e64 v142, v154, v178, s[44:45]
	v_pk_fma_f32 v[134:135], v[134:135], v[90:91], v[140:141]
	v_cndmask_b32_e64 v141, v155, v181, s[40:41]
	v_cndmask_b32_e64 v140, v153, v180, s[40:41]
	v_pk_mul_f32 v[142:143], v[80:81], v[142:143]
	v_mov_b32_dpp v178, v130 row_ror:2 row_mask:0xf bank_mask:0xf bound_ctrl:1
	v_mov_b32_dpp v180, v131 row_ror:2 row_mask:0xf bank_mask:0xf bound_ctrl:1
	v_pk_fma_f32 v[140:141], v[84:85], v[140:141], v[142:143]
	v_mov_b32_dpp v157, v130 row_ror:1 row_mask:0xf bank_mask:0xf bound_ctrl:1
	v_mov_b32_dpp v179, v131 row_ror:1 row_mask:0xf bank_mask:0xf bound_ctrl:1
	v_cndmask_b32_e64 v143, v180, v175, s[44:45]
	v_cndmask_b32_e64 v142, v178, v174, s[44:45]
	v_pk_fma_f32 v[136:137], v[136:137], v[92:93], v[140:141]
	v_cndmask_b32_e64 v141, v179, v177, s[40:41]
	v_cndmask_b32_e64 v140, v157, v176, s[40:41]
	v_pk_mul_f32 v[142:143], v[66:67], v[142:143]
	v_mov_b32_dpp v175, v132 row_ror:2 row_mask:0xf bank_mask:0xf bound_ctrl:1
	v_mov_b32_dpp v177, v133 row_ror:2 row_mask:0xf bank_mask:0xf bound_ctrl:1
	v_pk_fma_f32 v[140:141], v[70:71], v[140:141], v[142:143]
	v_mov_b32_dpp v174, v132 row_ror:1 row_mask:0xf bank_mask:0xf bound_ctrl:1
	v_mov_b32_dpp v176, v133 row_ror:1 row_mask:0xf bank_mask:0xf bound_ctrl:1
	v_cndmask_b32_e64 v143, v177, v171, s[44:45]
	v_cndmask_b32_e64 v142, v175, v170, s[44:45]
	v_pk_fma_f32 v[140:141], v[130:131], v[74:75], v[140:141]
	v_cndmask_b32_e64 v131, v176, v173, s[40:41]
	v_cndmask_b32_e64 v130, v174, v172, s[40:41]
	v_pk_mul_f32 v[142:143], v[68:69], v[142:143]
	s_mov_b32 s28, 0x3e6d3388
	v_pk_fma_f32 v[130:131], v[72:73], v[130:131], v[142:143]
	s_mov_b32 s20, 0xbf38aa3b
	v_pk_fma_f32 v[132:133], v[132:133], v[76:77], v[130:131]
	s_mov_b32 s8, 0xbf3a00e3
	v_and_b32_e32 v143, 0x7fffffff, v133
	v_and_b32_e32 v142, 0x7fffffff, v132
	v_pk_fma_f32 v[142:143], v[142:143], s[28:29], 1.0 op_sel_hi:[1,0,0]
	v_pk_mul_f32 v[130:131], v[132:133], v[132:133]
	v_rcp_f32_e32 v142, v142
	v_rcp_f32_e32 v143, v143
	v_pk_mul_f32 v[130:131], v[130:131], s[20:21] op_sel_hi:[1,0]
	s_mov_b32 s78, 0x3f07dc22
	v_exp_f32_e32 v144, v130
	v_exp_f32_e32 v145, v131
	v_mov_b64_e32 v[130:131], s[8:9]
	v_pk_fma_f32 v[146:147], v[142:143], s[78:79], v[130:131] op_sel_hi:[1,0,0]
	s_mov_b32 s88, 0x3f35f0e3
	v_pk_fma_f32 v[146:147], v[142:143], v[146:147], s[88:89] op_sel_hi:[1,1,0]
	s_mov_b32 s90, 0xbe11a98e
	v_pk_fma_f32 v[146:147], v[142:143], v[146:147], s[90:91] op_sel_hi:[1,1,0]
	s_mov_b32 s92, 0x3e027906
	v_pk_fma_f32 v[146:147], v[142:143], v[146:147], s[92:93] op_sel_hi:[1,1,0]
	v_cmp_gt_f32_e32 vcc, 0, v133
	v_pk_mul_f32 v[142:143], v[142:143], v[146:147]
	v_or_b32_e32 v148, 16, v192
	v_pk_mul_f32 v[142:143], v[144:145], v[142:143]
	s_movk_i32 s16, 0x1600
	v_pk_mul_f32 v[144:145], v[132:133], v[142:143]
	v_pk_fma_f32 v[142:143], v[132:133], v[142:143], v[132:133] neg_lo:[1,0,0] neg_hi:[1,0,0]
	v_mov_b32_dpp v146, v115 row_ror:2 row_mask:0xf bank_mask:0xf bound_ctrl:1
	v_cndmask_b32_e32 v133, v143, v145, vcc
	v_mul_f32_e32 v145, v129, v133
	v_cmp_gt_f32_e32 vcc, 0, v132
	v_and_b32_e32 v133, 0x7fffffff, v141
	v_and_b32_e32 v132, 0x7fffffff, v140
	v_pk_fma_f32 v[132:133], v[132:133], s[28:29], 1.0 op_sel_hi:[1,0,0]
	v_cndmask_b32_e32 v129, v142, v144, vcc
	v_rcp_f32_e32 v132, v132
	v_rcp_f32_e32 v133, v133
	v_mul_f32_e32 v144, v128, v129
	v_pk_mul_f32 v[128:129], v[140:141], v[140:141]
	v_cmp_gt_f32_e32 vcc, 0, v141
	v_pk_mul_f32 v[128:129], v[128:129], s[20:21] op_sel_hi:[1,0]
	v_pk_fma_f32 v[142:143], v[132:133], s[78:79], v[130:131] op_sel_hi:[1,0,0]
	v_exp_f32_e32 v128, v128
	v_exp_f32_e32 v129, v129
	v_pk_fma_f32 v[142:143], v[132:133], v[142:143], s[88:89] op_sel_hi:[1,1,0]
	v_mov_b32_dpp v147, v116 row_ror:1 row_mask:0xf bank_mask:0xf bound_ctrl:1
	v_pk_fma_f32 v[142:143], v[132:133], v[142:143], s[90:91] op_sel_hi:[1,1,0]
	s_nop 0
	v_pk_fma_f32 v[142:143], v[132:133], v[142:143], s[92:93] op_sel_hi:[1,1,0]
	s_nop 0
	v_pk_mul_f32 v[132:133], v[132:133], v[142:143]
	v_mov_b32_dpp v142, v121 row_ror:2 row_mask:0xf bank_mask:0xf bound_ctrl:1
	v_pk_mul_f32 v[128:129], v[128:129], v[132:133]
	v_mov_b32_dpp v143, v114 row_ror:1 row_mask:0xf bank_mask:0xf bound_ctrl:1
	v_pk_mul_f32 v[132:133], v[140:141], v[128:129]
	v_pk_fma_f32 v[128:129], v[140:141], v[128:129], v[140:141] neg_lo:[1,0,0] neg_hi:[1,0,0]
	s_nop 0
	v_cndmask_b32_e32 v129, v129, v133, vcc
	v_cmp_gt_f32_e32 vcc, 0, v140
	v_mul_f32_e32 v141, v127, v129
	v_and_b32_e32 v129, 0x7fffffff, v137
	v_cndmask_b32_e32 v127, v128, v132, vcc
; __device__ __forceinline__ unsigned cvt_pk_bf16(float lo, float hi) { unsigned r; asm volatile("v_cvt_pk_bf16_f32 %0, %1, %2" : "=v"(r) : "v"(lo), "v"(hi)); return r; }
;     __device__ __forceinline__ void operator()(const f32x4 (&acc)[2][2][4][2], const Unit& u, int wr, int wc, int fr, int fq) const {
;     ...
;                 for (int q = 0; q < 8; ++q) {
;                     const float r1 = __int_as_float(__builtin_amdgcn_mov_dpp(__float_as_int(x[q]), 0x121, 0xF, 0xF, true));
;                     const float r2 = __int_as_float(__builtin_amdgcn_mov_dpp(__float_as_int(x[q]), 0x122, 0xF, 0xF, true));
;                     const float x1 = (fr == 0) ? p1[q] : r1, x2 = (fr < 2) ? p2[q] : r2;
;                     y[q] = w0[q] * x2 + w1[q] * x1 + w2[q] * x[q]; p1[q] = r1; p2[q] = r2; }
; #pragma unroll
;                 for (int q = 0; q < 8; q += 2) { const f32x2 gq = gelu_pk((f32x2){y[q], y[q + 1]}); y[q] = gq.x * mu[q]; y[q + 1] = gq.y * mu[q + 1]; }
;                 const bool lo = (m == 0) && (fr < 2);
;                 if (!lo) { u32x4 w; w.x = cvt_pk_bf16(y[0], y[1]); w.y = cvt_pk_bf16(y[2], y[3]); w.z = cvt_pk_bf16(y[4], y[5]); w.w = cvt_pk_bf16(y[6], y[7]); *(u32x4*)(ACT + row * dff + c0) = w; }
	v_and_b32_e32 v128, 0x7fffffff, v136
	v_pk_fma_f32 v[128:129], v[128:129], s[28:29], 1.0 op_sel_hi:[1,0,0]
	v_mul_f32_e32 v140, v126, v127
	v_rcp_f32_e32 v128, v128
	v_rcp_f32_e32 v129, v129
	v_pk_mul_f32 v[126:127], v[136:137], v[136:137]
	v_cmp_gt_f32_e32 vcc, 0, v137
	v_pk_mul_f32 v[126:127], v[126:127], s[20:21] op_sel_hi:[1,0]
	v_pk_fma_f32 v[132:133], v[128:129], s[78:79], v[130:131] op_sel_hi:[1,0,0]
	v_exp_f32_e32 v126, v126
	v_exp_f32_e32 v127, v127
	v_pk_fma_f32 v[132:133], v[128:129], v[132:133], s[88:89] op_sel_hi:[1,1,0]
	s_nop 0
	v_pk_fma_f32 v[132:133], v[128:129], v[132:133], s[90:91] op_sel_hi:[1,1,0]
	s_nop 0
	v_pk_fma_f32 v[132:133], v[128:129], v[132:133], s[92:93] op_sel_hi:[1,1,0]
	s_nop 0
	v_pk_mul_f32 v[128:129], v[128:129], v[132:133]
	s_nop 0
	v_pk_mul_f32 v[126:127], v[126:127], v[128:129]
	s_nop 0
	v_pk_mul_f32 v[128:129], v[136:137], v[126:127]
	v_pk_fma_f32 v[126:127], v[136:137], v[126:127], v[136:137] neg_lo:[1,0,0] neg_hi:[1,0,0]
	v_mov_b32_dpp v137, v120 row_ror:1 row_mask:0xf bank_mask:0xf bound_ctrl:1
	v_cndmask_b32_e32 v127, v127, v129, vcc
	v_cmp_gt_f32_e32 vcc, 0, v136
	v_mul_f32_e32 v132, v125, v127
	v_and_b32_e32 v127, 0x7fffffff, v135
	v_cndmask_b32_e32 v125, v126, v128, vcc
	v_and_b32_e32 v126, 0x7fffffff, v134
	v_pk_fma_f32 v[126:127], v[126:127], s[28:29], 1.0 op_sel_hi:[1,0,0]
	v_mul_f32_e32 v133, v124, v125
	v_rcp_f32_e32 v126, v126
	v_rcp_f32_e32 v127, v127
	v_pk_mul_f32 v[124:125], v[134:135], v[134:135]
	v_cmp_gt_f32_e32 vcc, 0, v135
	v_pk_mul_f32 v[124:125], v[124:125], s[20:21] op_sel_hi:[1,0]
	v_pk_fma_f32 v[128:129], v[126:127], s[78:79], v[130:131] op_sel_hi:[1,0,0]
	v_exp_f32_e32 v124, v124
	v_exp_f32_e32 v125, v125
	v_pk_fma_f32 v[128:129], v[126:127], v[128:129], s[88:89] op_sel_hi:[1,1,0]
	v_mov_b32_dpp v136, v119 row_ror:2 row_mask:0xf bank_mask:0xf bound_ctrl:1
	v_pk_fma_f32 v[128:129], v[126:127], v[128:129], s[90:91] op_sel_hi:[1,1,0]
	s_nop 0
	v_pk_fma_f32 v[128:129], v[126:127], v[128:129], s[92:93] op_sel_hi:[1,1,0]
	s_nop 0
	v_pk_mul_f32 v[126:127], v[126:127], v[128:129]
	s_nop 0
	v_pk_mul_f32 v[124:125], v[124:125], v[126:127]
	s_nop 0
	v_pk_mul_f32 v[126:127], v[134:135], v[124:125]
	v_pk_fma_f32 v[124:125], v[134:135], v[124:125], v[134:135] neg_lo:[1,0,0] neg_hi:[1,0,0]
	v_mov_b32_dpp v135, v119 row_ror:1 row_mask:0xf bank_mask:0xf bound_ctrl:1
	v_cndmask_b32_e32 v125, v125, v127, vcc
	v_cmp_gt_f32_e32 vcc, 0, v134
	v_mul_f32_e32 v123, v123, v125
	v_mov_b32_dpp v134, v118 row_ror:2 row_mask:0xf bank_mask:0xf bound_ctrl:1
	v_cndmask_b32_e32 v124, v124, v126, vcc
	v_mul_f32_e32 v122, v122, v124
	v_cvt_pk_bf16_f32 v124, v122, v123
	v_mov_b64_e32 v[122:123], s[4:5]
	v_mad_i64_i32 v[128:129], s[8:9], v148, s16, v[122:123]
	v_cvt_pk_bf16_f32 v125, v133, v132
	v_cvt_pk_bf16_f32 v126, v140, v141
	v_cvt_pk_bf16_f32 v127, v144, v145
	v_lshl_add_u64 v[128:129], v[128:129], 0, v[138:139]
	global_store_dwordx4 v[128:129], v[124:127], off
	v_mov_b32_dpp v133, v118 row_ror:1 row_mask:0xf bank_mask:0xf bound_ctrl:1
	v_mov_b32_dpp v140, v120 row_ror:2 row_mask:0xf bank_mask:0xf bound_ctrl:1
	v_cndmask_b32_e64 v127, v136, v152, s[44:45]
	v_cndmask_b32_e64 v126, v134, v150, s[44:45]
	v_cndmask_b32_e64 v125, v135, v151, s[40:41]
	v_cndmask_b32_e64 v124, v133, v149, s[40:41]
	v_pk_mul_f32 v[126:127], v[78:79], v[126:127]
	v_mov_b32_dpp v141, v121 row_ror:1 row_mask:0xf bank_mask:0xf bound_ctrl:1
	v_pk_fma_f32 v[124:125], v[82:83], v[124:125], v[126:127]
	v_cndmask_b32_e64 v127, v142, v156, s[44:45]
	v_cndmask_b32_e64 v126, v140, v154, s[44:45]
	v_pk_fma_f32 v[118:119], v[118:119], v[90:91], v[124:125]
	v_cndmask_b32_e64 v125, v141, v155, s[40:41]
	v_cndmask_b32_e64 v124, v137, v153, s[40:41]
	v_pk_mul_f32 v[126:127], v[80:81], v[126:127]
	v_mov_b32_dpp v144, v114 row_ror:2 row_mask:0xf bank_mask:0xf bound_ctrl:1
	v_pk_fma_f32 v[124:125], v[84:85], v[124:125], v[126:127]
	v_mov_b32_dpp v145, v115 row_ror:1 row_mask:0xf bank_mask:0xf bound_ctrl:1
	v_cndmask_b32_e64 v127, v146, v180, s[44:45]
	v_cndmask_b32_e64 v126, v144, v178, s[44:45]
	v_pk_fma_f32 v[120:121], v[120:121], v[92:93], v[124:125]
	v_cndmask_b32_e64 v125, v145, v179, s[40:41]
	v_cndmask_b32_e64 v124, v143, v157, s[40:41]
	v_pk_mul_f32 v[126:127], v[66:67], v[126:127]
	v_mov_b32_dpp v148, v116 row_ror:2 row_mask:0xf bank_mask:0xf bound_ctrl:1
	v_mov_b32_dpp v150, v117 row_ror:2 row_mask:0xf bank_mask:0xf bound_ctrl:1
	v_pk_fma_f32 v[124:125], v[70:71], v[124:125], v[126:127]
	v_mov_b32_dpp v149, v117 row_ror:1 row_mask:0xf bank_mask:0xf bound_ctrl:1
	v_cndmask_b32_e64 v127, v150, v177, s[44:45]
	v_cndmask_b32_e64 v126, v148, v175, s[44:45]
	v_pk_fma_f32 v[114:115], v[114:115], v[74:75], v[124:125]
	v_cndmask_b32_e64 v125, v149, v176, s[40:41]
	v_cndmask_b32_e64 v124, v147, v174, s[40:41]
	v_pk_mul_f32 v[126:127], v[68:69], v[126:127]
	v_or_b32_e32 v132, 32, v192
	v_pk_fma_f32 v[124:125], v[72:73], v[124:125], v[126:127]
	s_nop 0
	v_pk_fma_f32 v[116:117], v[116:117], v[76:77], v[124:125]
	s_nop 0
	v_and_b32_e32 v127, 0x7fffffff, v117
	v_and_b32_e32 v126, 0x7fffffff, v116
	v_pk_fma_f32 v[126:127], v[126:127], s[28:29], 1.0 op_sel_hi:[1,0,0]
	v_pk_mul_f32 v[124:125], v[116:117], v[116:117]
	v_rcp_f32_e32 v126, v126
	v_rcp_f32_e32 v127, v127
	v_pk_mul_f32 v[124:125], v[124:125], s[20:21] op_sel_hi:[1,0]
	v_cmp_gt_f32_e32 vcc, 0, v117
	v_exp_f32_e32 v124, v124
	v_pk_fma_f32 v[128:129], v[126:127], s[78:79], v[130:131] op_sel_hi:[1,0,0]
	v_exp_f32_e32 v125, v125
	v_pk_fma_f32 v[128:129], v[126:127], v[128:129], s[88:89] op_sel_hi:[1,1,0]
	s_nop 0
	v_pk_fma_f32 v[128:129], v[126:127], v[128:129], s[90:91] op_sel_hi:[1,1,0]
	s_nop 0
; __device__ __forceinline__ unsigned cvt_pk_bf16(float lo, float hi) { unsigned r; asm volatile("v_cvt_pk_bf16_f32 %0, %1, %2" : "=v"(r) : "v"(lo), "v"(hi)); return r; }
;     __device__ __forceinline__ void operator()(const f32x4 (&acc)[2][2][4][2], const Unit& u, int wr, int wc, int fr, int fq) const {
;     ...
;                 for (int q = 0; q < 8; ++q) {
;                     const float r1 = __int_as_float(__builtin_amdgcn_mov_dpp(__float_as_int(x[q]), 0x121, 0xF, 0xF, true));
;                     const float r2 = __int_as_float(__builtin_amdgcn_mov_dpp(__float_as_int(x[q]), 0x122, 0xF, 0xF, true));
;                     const float x1 = (fr == 0) ? p1[q] : r1, x2 = (fr < 2) ? p2[q] : r2;
;                     y[q] = w0[q] * x2 + w1[q] * x1 + w2[q] * x[q]; p1[q] = r1; p2[q] = r2; }
; #pragma unroll
;                 for (int q = 0; q < 8; q += 2) { const f32x2 gq = gelu_pk((f32x2){y[q], y[q + 1]}); y[q] = gq.x * mu[q]; y[q + 1] = gq.y * mu[q + 1]; }
;                 const bool lo = (m == 0) && (fr < 2);
;                 if (!lo) { u32x4 w; w.x = cvt_pk_bf16(y[0], y[1]); w.y = cvt_pk_bf16(y[2], y[3]); w.z = cvt_pk_bf16(y[4], y[5]); w.w = cvt_pk_bf16(y[6], y[7]); *(u32x4*)(ACT + row * dff + c0) = w; }
	v_pk_fma_f32 v[128:129], v[126:127], v[128:129], s[92:93] op_sel_hi:[1,1,0]
	s_nop 0
	v_pk_mul_f32 v[126:127], v[126:127], v[128:129]
	s_nop 0
	v_pk_mul_f32 v[124:125], v[124:125], v[126:127]
	s_nop 0
	v_pk_mul_f32 v[126:127], v[116:117], v[124:125]
	v_pk_fma_f32 v[124:125], v[116:117], v[124:125], v[116:117] neg_lo:[1,0,0] neg_hi:[1,0,0]
	s_nop 0
	v_cndmask_b32_e32 v117, v125, v127, vcc
	v_mul_f32_e32 v127, v113, v117
	v_cmp_gt_f32_e32 vcc, 0, v116
	v_and_b32_e32 v117, 0x7fffffff, v115
	v_and_b32_e32 v116, 0x7fffffff, v114
	v_pk_fma_f32 v[116:117], v[116:117], s[28:29], 1.0 op_sel_hi:[1,0,0]
	v_cndmask_b32_e32 v113, v124, v126, vcc
	v_rcp_f32_e32 v116, v116
	v_rcp_f32_e32 v117, v117
	v_mul_f32_e32 v126, v112, v113
	v_pk_mul_f32 v[112:113], v[114:115], v[114:115]
	v_cmp_gt_f32_e32 vcc, 0, v115
	v_pk_mul_f32 v[112:113], v[112:113], s[20:21] op_sel_hi:[1,0]
	v_pk_fma_f32 v[124:125], v[116:117], s[78:79], v[130:131] op_sel_hi:[1,0,0]
	v_exp_f32_e32 v112, v112
	v_exp_f32_e32 v113, v113
	v_pk_fma_f32 v[124:125], v[116:117], v[124:125], s[88:89] op_sel_hi:[1,1,0]
	s_nop 0
	v_pk_fma_f32 v[124:125], v[116:117], v[124:125], s[90:91] op_sel_hi:[1,1,0]
	s_nop 0
	v_pk_fma_f32 v[124:125], v[116:117], v[124:125], s[92:93] op_sel_hi:[1,1,0]
	s_nop 0
	v_pk_mul_f32 v[116:117], v[116:117], v[124:125]
	s_nop 0
	v_pk_mul_f32 v[112:113], v[112:113], v[116:117]
	s_nop 0
	v_pk_mul_f32 v[116:117], v[114:115], v[112:113]
	v_pk_fma_f32 v[112:113], v[114:115], v[112:113], v[114:115] neg_lo:[1,0,0] neg_hi:[1,0,0]
	s_nop 0
	v_cndmask_b32_e32 v113, v113, v117, vcc
	v_cmp_gt_f32_e32 vcc, 0, v114
	v_mul_f32_e32 v117, v111, v113
	v_and_b32_e32 v113, 0x7fffffff, v121
	v_cndmask_b32_e32 v111, v112, v116, vcc
	v_and_b32_e32 v112, 0x7fffffff, v120
	v_pk_fma_f32 v[112:113], v[112:113], s[28:29], 1.0 op_sel_hi:[1,0,0]
	v_mul_f32_e32 v116, v110, v111
	v_rcp_f32_e32 v112, v112
	v_rcp_f32_e32 v113, v113
	v_pk_mul_f32 v[110:111], v[120:121], v[120:121]
	v_cmp_gt_f32_e32 vcc, 0, v121
	v_pk_mul_f32 v[110:111], v[110:111], s[20:21] op_sel_hi:[1,0]
	v_pk_fma_f32 v[114:115], v[112:113], s[78:79], v[130:131] op_sel_hi:[1,0,0]
	v_exp_f32_e32 v110, v110
	v_exp_f32_e32 v111, v111
	v_pk_fma_f32 v[114:115], v[112:113], v[114:115], s[88:89] op_sel_hi:[1,1,0]
	s_nop 0
	v_pk_fma_f32 v[114:115], v[112:113], v[114:115], s[90:91] op_sel_hi:[1,1,0]
	s_nop 0
	v_pk_fma_f32 v[114:115], v[112:113], v[114:115], s[92:93] op_sel_hi:[1,1,0]
	s_nop 0
	v_pk_mul_f32 v[112:113], v[112:113], v[114:115]
	s_nop 0
	v_pk_mul_f32 v[110:111], v[110:111], v[112:113]
	s_nop 0
	v_pk_mul_f32 v[112:113], v[120:121], v[110:111]
	v_pk_fma_f32 v[110:111], v[120:121], v[110:111], v[120:121] neg_lo:[1,0,0] neg_hi:[1,0,0]
	s_nop 0
	v_cndmask_b32_e32 v111, v111, v113, vcc
	v_cmp_gt_f32_e32 vcc, 0, v120
	v_mul_f32_e32 v114, v109, v111
	v_and_b32_e32 v111, 0x7fffffff, v119
	v_cndmask_b32_e32 v109, v110, v112, vcc
	v_and_b32_e32 v110, 0x7fffffff, v118
	v_pk_fma_f32 v[110:111], v[110:111], s[28:29], 1.0 op_sel_hi:[1,0,0]
	v_mul_f32_e32 v115, v108, v109
	v_rcp_f32_e32 v110, v110
	v_rcp_f32_e32 v111, v111
	v_pk_mul_f32 v[108:109], v[118:119], v[118:119]
	v_cmp_gt_f32_e32 vcc, 0, v119
	v_pk_mul_f32 v[108:109], v[108:109], s[20:21] op_sel_hi:[1,0]
	v_pk_fma_f32 v[112:113], v[110:111], s[78:79], v[130:131] op_sel_hi:[1,0,0]
	v_exp_f32_e32 v108, v108
	v_exp_f32_e32 v109, v109
	v_pk_fma_f32 v[112:113], v[110:111], v[112:113], s[88:89] op_sel_hi:[1,1,0]
	s_nop 0
	v_pk_fma_f32 v[112:113], v[110:111], v[112:113], s[90:91] op_sel_hi:[1,1,0]
	s_nop 0
	v_pk_fma_f32 v[112:113], v[110:111], v[112:113], s[92:93] op_sel_hi:[1,1,0]
	s_nop 0
	v_pk_mul_f32 v[110:111], v[110:111], v[112:113]
	v_mov_b32_dpp v112, v104 row_ror:2 row_mask:0xf bank_mask:0xf bound_ctrl:1
	v_pk_mul_f32 v[108:109], v[108:109], v[110:111]
	v_mov_b32_dpp v113, v105 row_ror:2 row_mask:0xf bank_mask:0xf bound_ctrl:1
	v_pk_mul_f32 v[110:111], v[118:119], v[108:109]
	v_pk_fma_f32 v[108:109], v[118:119], v[108:109], v[118:119] neg_lo:[1,0,0] neg_hi:[1,0,0]
	v_cndmask_b32_e64 v113, v113, v142, s[44:45]
	v_cndmask_b32_e32 v109, v109, v111, vcc
	v_cmp_gt_f32_e32 vcc, 0, v118
	v_mul_f32_e32 v107, v107, v109
	v_cndmask_b32_e64 v112, v112, v140, s[44:45]
	v_cndmask_b32_e32 v108, v108, v110, vcc
	v_mad_i64_i32 v[110:111], s[8:9], v132, s16, v[122:123]
	v_mul_f32_e32 v106, v106, v108
	v_lshl_add_u64 v[110:111], v[110:111], 0, v[138:139]
	v_cvt_pk_bf16_f32 v106, v106, v107
	v_cvt_pk_bf16_f32 v107, v115, v114
	v_cvt_pk_bf16_f32 v108, v116, v117
	v_cvt_pk_bf16_f32 v109, v126, v127
	global_store_dwordx4 v[110:111], v[106:109], off
	s_nop 0
	v_mov_b32_dpp v110, v102 row_ror:2 row_mask:0xf bank_mask:0xf bound_ctrl:1
	v_mov_b32_dpp v111, v103 row_ror:2 row_mask:0xf bank_mask:0xf bound_ctrl:1
	v_mov_b32_dpp v107, v102 row_ror:1 row_mask:0xf bank_mask:0xf bound_ctrl:1
	v_mov_b32_dpp v108, v103 row_ror:1 row_mask:0xf bank_mask:0xf bound_ctrl:1
	v_cndmask_b32_e64 v111, v111, v136, s[44:45]
	v_cndmask_b32_e64 v110, v110, v134, s[44:45]
	v_cndmask_b32_e64 v109, v108, v135, s[40:41]
	v_cndmask_b32_e64 v108, v107, v133, s[40:41]
	v_pk_mul_f32 v[110:111], v[78:79], v[110:111]
	v_mov_b32_dpp v107, v104 row_ror:1 row_mask:0xf bank_mask:0xf bound_ctrl:1
	v_pk_fma_f32 v[108:109], v[82:83], v[108:109], v[110:111]
	v_mov_b32_dpp v110, v105 row_ror:1 row_mask:0xf bank_mask:0xf bound_ctrl:1
	v_cndmask_b32_e64 v111, v110, v141, s[40:41]
	v_cndmask_b32_e64 v110, v107, v137, s[40:41]
	v_pk_mul_f32 v[112:113], v[80:81], v[112:113]
	v_mov_b32_dpp v114, v98 row_ror:2 row_mask:0xf bank_mask:0xf bound_ctrl:1
	v_mov_b32_dpp v115, v99 row_ror:2 row_mask:0xf bank_mask:0xf bound_ctrl:1
	v_pk_fma_f32 v[110:111], v[84:85], v[110:111], v[112:113]
; __device__ __forceinline__ unsigned cvt_pk_bf16(float lo, float hi) { unsigned r; asm volatile("v_cvt_pk_bf16_f32 %0, %1, %2" : "=v"(r) : "v"(lo), "v"(hi)); return r; }
;     __device__ __forceinline__ void operator()(const f32x4 (&acc)[2][2][4][2], const Unit& u, int wr, int wc, int fr, int fq) const {
;     ...
;                 for (int q = 0; q < 8; ++q) {
;                     const float r1 = __int_as_float(__builtin_amdgcn_mov_dpp(__float_as_int(x[q]), 0x121, 0xF, 0xF, true));
;                     const float r2 = __int_as_float(__builtin_amdgcn_mov_dpp(__float_as_int(x[q]), 0x122, 0xF, 0xF, true));
;                     const float x1 = (fr == 0) ? p1[q] : r1, x2 = (fr < 2) ? p2[q] : r2;
;                     y[q] = w0[q] * x2 + w1[q] * x1 + w2[q] * x[q]; p1[q] = r1; p2[q] = r2; }
; #pragma unroll
;                 for (int q = 0; q < 8; q += 2) { const f32x2 gq = gelu_pk((f32x2){y[q], y[q + 1]}); y[q] = gq.x * mu[q]; y[q + 1] = gq.y * mu[q + 1]; }
;                 const bool lo = (m == 0) && (fr < 2);
;                 if (!lo) { u32x4 w; w.x = cvt_pk_bf16(y[0], y[1]); w.y = cvt_pk_bf16(y[2], y[3]); w.z = cvt_pk_bf16(y[4], y[5]); w.w = cvt_pk_bf16(y[6], y[7]); *(u32x4*)(ACT + row * dff + c0) = w; }
;                 if (lo || ((m == 3) && (fr >= 14))) {
;                     u32x4 wx, wm; wx.x = cvt_pk_bf16(x[0], x[1]); wx.y = cvt_pk_bf16(x[2], x[3]); wx.z = cvt_pk_bf16(x[4], x[5]); wx.w = cvt_pk_bf16(x[6], x[7]);
;                     wm.x = cvt_pk_bf16(mu[0], mu[1]); wm.y = cvt_pk_bf16(mu[2], mu[3]); wm.z = cvt_pk_bf16(mu[4], mu[5]); wm.w = cvt_pk_bf16(mu[6], mu[7]);
;                     *(u32x4*)(UP + row * upw + c0) = wx; *(u32x4*)(UP + row * upw + dff + c0) = wm; }
	v_mov_b32_dpp v107, v98 row_ror:1 row_mask:0xf bank_mask:0xf bound_ctrl:1
	v_mov_b32_dpp v112, v99 row_ror:1 row_mask:0xf bank_mask:0xf bound_ctrl:1
	v_cndmask_b32_e64 v115, v115, v146, s[44:45]
	v_cndmask_b32_e64 v114, v114, v144, s[44:45]
	v_cndmask_b32_e64 v113, v112, v145, s[40:41]
	v_cndmask_b32_e64 v112, v107, v143, s[40:41]
	v_pk_mul_f32 v[114:115], v[66:67], v[114:115]
	v_mov_b32_dpp v116, v100 row_ror:2 row_mask:0xf bank_mask:0xf bound_ctrl:1
	v_mov_b32_dpp v117, v101 row_ror:2 row_mask:0xf bank_mask:0xf bound_ctrl:1
	v_pk_fma_f32 v[112:113], v[70:71], v[112:113], v[114:115]
	v_mov_b32_dpp v107, v100 row_ror:1 row_mask:0xf bank_mask:0xf bound_ctrl:1
	v_mov_b32_dpp v114, v101 row_ror:1 row_mask:0xf bank_mask:0xf bound_ctrl:1
	v_cndmask_b32_e64 v117, v117, v150, s[44:45]
	v_cndmask_b32_e64 v116, v116, v148, s[44:45]
	v_cndmask_b32_e64 v115, v114, v149, s[40:41]
	v_cndmask_b32_e64 v114, v107, v147, s[40:41]
	v_pk_mul_f32 v[116:117], v[68:69], v[116:117]
	v_pk_fma_f32 v[112:113], v[98:99], v[74:75], v[112:113]
	v_pk_fma_f32 v[114:115], v[72:73], v[114:115], v[116:117]
	v_pk_fma_f32 v[110:111], v[104:105], v[92:93], v[110:111]
	v_pk_fma_f32 v[114:115], v[100:101], v[76:77], v[114:115]
	v_pk_fma_f32 v[108:109], v[102:103], v[90:91], v[108:109]
	v_and_b32_e32 v119, 0x7fffffff, v115
	v_and_b32_e32 v118, 0x7fffffff, v114
	v_pk_fma_f32 v[118:119], v[118:119], s[28:29], 1.0 op_sel_hi:[1,0,0]
	v_pk_mul_f32 v[116:117], v[114:115], v[114:115]
	v_rcp_f32_e32 v118, v118
	v_rcp_f32_e32 v119, v119
	v_pk_mul_f32 v[116:117], v[116:117], s[20:21] op_sel_hi:[1,0]
	v_cmp_gt_f32_e32 vcc, 0, v115
	v_exp_f32_e32 v116, v116
	v_pk_fma_f32 v[120:121], v[118:119], s[78:79], v[130:131] op_sel_hi:[1,0,0]
	v_exp_f32_e32 v117, v117
	v_pk_fma_f32 v[120:121], v[118:119], v[120:121], s[88:89] op_sel_hi:[1,1,0]
	v_or_b32_e32 v106, 48, v192
	v_pk_fma_f32 v[120:121], v[118:119], v[120:121], s[90:91] op_sel_hi:[1,1,0]
	s_nop 0
	v_pk_fma_f32 v[120:121], v[118:119], v[120:121], s[92:93] op_sel_hi:[1,1,0]
	s_nop 0
	v_pk_mul_f32 v[118:119], v[118:119], v[120:121]
	s_nop 0
	v_pk_mul_f32 v[116:117], v[116:117], v[118:119]
	s_nop 0
	v_pk_mul_f32 v[118:119], v[114:115], v[116:117]
	v_pk_fma_f32 v[116:117], v[114:115], v[116:117], v[114:115] neg_lo:[1,0,0] neg_hi:[1,0,0]
	s_nop 0
	v_cndmask_b32_e32 v107, v117, v119, vcc
	v_cmp_gt_f32_e32 vcc, 0, v114
	v_and_b32_e32 v117, 0x7fffffff, v113
	v_mul_f32_e32 v107, v89, v107
	v_cndmask_b32_e32 v114, v116, v118, vcc
	v_and_b32_e32 v116, 0x7fffffff, v112
	v_pk_fma_f32 v[116:117], v[116:117], s[28:29], 1.0 op_sel_hi:[1,0,0]
	v_mul_f32_e32 v120, v88, v114
	v_rcp_f32_e32 v116, v116
	v_rcp_f32_e32 v117, v117
	v_pk_mul_f32 v[114:115], v[112:113], v[112:113]
	v_cmp_gt_f32_e32 vcc, 0, v113
	v_pk_mul_f32 v[114:115], v[114:115], s[20:21] op_sel_hi:[1,0]
	v_pk_fma_f32 v[118:119], v[116:117], s[78:79], v[130:131] op_sel_hi:[1,0,0]
	v_exp_f32_e32 v114, v114
	v_exp_f32_e32 v115, v115
	v_pk_fma_f32 v[118:119], v[116:117], v[118:119], s[88:89] op_sel_hi:[1,1,0]
	s_nop 0
	v_pk_fma_f32 v[118:119], v[116:117], v[118:119], s[90:91] op_sel_hi:[1,1,0]
	s_nop 0
	v_pk_fma_f32 v[118:119], v[116:117], v[118:119], s[92:93] op_sel_hi:[1,1,0]
	s_nop 0
	v_pk_mul_f32 v[116:117], v[116:117], v[118:119]
	s_nop 0
	v_pk_mul_f32 v[114:115], v[114:115], v[116:117]
	s_nop 0
	v_pk_mul_f32 v[116:117], v[112:113], v[114:115]
	v_pk_fma_f32 v[114:115], v[112:113], v[114:115], v[112:113] neg_lo:[1,0,0] neg_hi:[1,0,0]
	s_nop 0
	v_cndmask_b32_e32 v113, v115, v117, vcc
	v_cmp_gt_f32_e32 vcc, 0, v112
	v_and_b32_e32 v115, 0x7fffffff, v111
	v_mul_f32_e32 v118, v87, v113
	v_cndmask_b32_e32 v112, v114, v116, vcc
	v_and_b32_e32 v114, 0x7fffffff, v110
	v_pk_fma_f32 v[114:115], v[114:115], s[28:29], 1.0 op_sel_hi:[1,0,0]
	v_mul_f32_e32 v119, v86, v112
	v_rcp_f32_e32 v114, v114
	v_rcp_f32_e32 v115, v115
	v_pk_mul_f32 v[112:113], v[110:111], v[110:111]
	v_cmp_gt_f32_e32 vcc, 0, v111
	v_pk_mul_f32 v[112:113], v[112:113], s[20:21] op_sel_hi:[1,0]
	v_pk_fma_f32 v[116:117], v[114:115], s[78:79], v[130:131] op_sel_hi:[1,0,0]
	v_exp_f32_e32 v112, v112
	v_exp_f32_e32 v113, v113
	v_pk_fma_f32 v[116:117], v[114:115], v[116:117], s[88:89] op_sel_hi:[1,1,0]
	s_nop 0
	v_pk_fma_f32 v[116:117], v[114:115], v[116:117], s[90:91] op_sel_hi:[1,1,0]
	s_nop 0
	v_pk_fma_f32 v[116:117], v[114:115], v[116:117], s[92:93] op_sel_hi:[1,1,0]
	s_nop 0
	v_pk_mul_f32 v[114:115], v[114:115], v[116:117]
	s_nop 0
	v_pk_mul_f32 v[112:113], v[112:113], v[114:115]
	s_nop 0
	v_pk_mul_f32 v[114:115], v[110:111], v[112:113]
	v_pk_fma_f32 v[112:113], v[110:111], v[112:113], v[110:111] neg_lo:[1,0,0] neg_hi:[1,0,0]
	s_nop 0
	v_cndmask_b32_e32 v111, v113, v115, vcc
	v_cmp_gt_f32_e32 vcc, 0, v110
	v_and_b32_e32 v113, 0x7fffffff, v109
	v_mul_f32_e32 v116, v97, v111
	v_cndmask_b32_e32 v110, v112, v114, vcc
	v_and_b32_e32 v112, 0x7fffffff, v108
	v_pk_fma_f32 v[112:113], v[112:113], s[28:29], 1.0 op_sel_hi:[1,0,0]
	v_mul_f32_e32 v117, v96, v110
	v_rcp_f32_e32 v112, v112
	v_rcp_f32_e32 v113, v113
	v_pk_mul_f32 v[110:111], v[108:109], v[108:109]
	v_cmp_gt_f32_e32 vcc, 0, v109
	v_pk_mul_f32 v[110:111], v[110:111], s[20:21] op_sel_hi:[1,0]
	v_pk_fma_f32 v[114:115], v[112:113], s[78:79], v[130:131] op_sel_hi:[1,0,0]
	v_exp_f32_e32 v110, v110
	v_exp_f32_e32 v111, v111
	v_pk_fma_f32 v[114:115], v[112:113], v[114:115], s[88:89] op_sel_hi:[1,1,0]
	s_movk_i32 s20, 0x1600
	v_pk_fma_f32 v[114:115], v[112:113], v[114:115], s[90:91] op_sel_hi:[1,1,0]
	s_nop 0
	v_pk_fma_f32 v[114:115], v[112:113], v[114:115], s[92:93] op_sel_hi:[1,1,0]
	s_nop 0
	v_pk_mul_f32 v[112:113], v[112:113], v[114:115]
	s_nop 0
	v_pk_mul_f32 v[110:111], v[110:111], v[112:113]
	s_nop 0
	v_pk_mul_f32 v[112:113], v[108:109], v[110:111]
	v_pk_fma_f32 v[110:111], v[108:109], v[110:111], v[108:109] neg_lo:[1,0,0] neg_hi:[1,0,0]
	s_nop 0
	v_cndmask_b32_e32 v109, v111, v113, vcc
	v_cmp_gt_f32_e32 vcc, 0, v108
	v_mul_f32_e32 v109, v95, v109
	s_nop 0
	v_cndmask_b32_e32 v108, v110, v112, vcc
	v_mad_i64_i32 v[112:113], s[8:9], v106, s16, v[122:123]
	v_mul_f32_e32 v108, v94, v108
	v_lshl_add_u64 v[112:113], v[112:113], 0, v[138:139]
	v_cvt_pk_bf16_f32 v108, v108, v109
	v_cvt_pk_bf16_f32 v109, v117, v116
	v_cvt_pk_bf16_f32 v110, v119, v118
	v_cvt_pk_bf16_f32 v111, v120, v107
	global_store_dwordx4 v[112:113], v[108:111], off
	s_and_saveexec_b64 s[8:9], s[46:47]
	s_cbranch_execz .LBB0_1856
	v_cvt_pk_bf16_f32 v102, v102, v103
	v_cvt_pk_bf16_f32 v103, v104, v105
	v_cvt_pk_bf16_f32 v104, v98, v99
	v_cvt_pk_bf16_f32 v105, v100, v101
	v_cvt_pk_bf16_f32 v94, v94, v95
	v_cvt_pk_bf16_f32 v95, v96, v97
	v_cvt_pk_bf16_f32 v96, v86, v87
	v_mov_b64_e32 v[86:87], s[6:7]
	s_movk_i32 s16, 0x2c00
	v_mad_i64_i32 v[86:87], s[16:17], v106, s16, v[86:87]
	v_lshl_add_u64 v[86:87], v[168:169], 1, v[86:87]
	v_cvt_pk_bf16_f32 v97, v88, v89
	global_store_dwordx4 v[86:87], v[102:105], off
	v_add_co_u32_e32 v86, vcc, 0x1000, v86
	s_nop 1
	v_addc_co_u32_e32 v87, vcc, 0, v87, vcc
	global_store_dwordx4 v[86:87], v[94:97], off offset:1536
